# v89 plus: in the K-loop load segments the LDS-DMA issues come first (first reads as M0 wait-state fillers), the remaining fragment reads after
# baseline (speedup 1.0000x reference)
.LBB0_265:
	s_add_i32 m0, s33, 0xc000
	ds_read_b128 v[154:157], v161
	global_load_lds_dwordx4 v146, s[72:73]
	s_add_i32 m0, s33, 0xe000
	ds_read_b128 v[164:167], v161 offset:1024
	global_load_lds_dwordx4 v148, s[72:73]
	ds_read_b128 v[168:171], v161 offset:2048
	ds_read_b128 v[172:175], v161 offset:3072
	ds_read_b128 v[176:179], v162
	ds_read_b128 v[180:183], v162 offset:1024
	ds_read_b128 v[184:187], v162 offset:2048
	ds_read_b128 v[188:191], v162 offset:3072
	ds_read_b128 v[192:195], v163
	ds_read_b128 v[196:199], v163 offset:1024
	ds_read_b128 v[200:203], v163 offset:2048
	ds_read_b128 v[204:207], v163 offset:3072
	ds_read_b128 v[208:211], v163 offset:4096
	ds_read_b128 v[212:215], v163 offset:5120
	ds_read_b128 v[216:219], v163 offset:6144
	ds_read_b128 v[220:223], v163 offset:7168
	s_waitcnt vmcnt(8) lgkmcnt(0)
	s_barrier
	s_setprio 1
	v_mfma_f32_16x16x32_bf16 v[126:129], v[154:157], v[192:195], v[126:129]
	v_mfma_f32_16x16x32_bf16 v[126:129], v[164:167], v[196:199], v[126:129]
	s_add_u32 s12, s72, 0xfff00080
	v_mfma_f32_16x16x32_bf16 v[110:113], v[154:157], v[200:203], v[110:113]
	v_mfma_f32_16x16x32_bf16 v[110:113], v[164:167], v[204:207], v[110:113]
	s_addc_u32 s13, s73, -1
	v_mfma_f32_16x16x32_bf16 v[94:97], v[154:157], v[208:211], v[94:97]
	v_mfma_f32_16x16x32_bf16 v[94:97], v[164:167], v[212:215], v[94:97]
	s_cmp_eq_u32 s83, 60
	v_mfma_f32_16x16x32_bf16 v[78:81], v[154:157], v[216:219], v[78:81]
	v_mfma_f32_16x16x32_bf16 v[78:81], v[164:167], v[220:223], v[78:81]
	s_cselect_b32 s77, s55, s13
	v_mfma_f32_16x16x32_bf16 v[122:125], v[168:171], v[192:195], v[122:125]
	v_mfma_f32_16x16x32_bf16 v[122:125], v[172:175], v[196:199], v[122:125]
	s_cselect_b32 s76, s71, s12
	v_mfma_f32_16x16x32_bf16 v[106:109], v[168:171], v[200:203], v[106:109]
	v_mfma_f32_16x16x32_bf16 v[106:109], v[172:175], v[204:207], v[106:109]
	s_cselect_b32 s75, s53, s82
	v_mfma_f32_16x16x32_bf16 v[90:93], v[168:171], v[208:211], v[90:93]
	v_mfma_f32_16x16x32_bf16 v[90:93], v[172:175], v[212:215], v[90:93]
	s_cselect_b32 s74, s80, s81
	v_mfma_f32_16x16x32_bf16 v[74:77], v[168:171], v[216:219], v[74:77]
	v_mfma_f32_16x16x32_bf16 v[74:77], v[172:175], v[220:223], v[74:77]
	s_add_u32 s98, s74, 0x100000
	v_mfma_f32_16x16x32_bf16 v[118:121], v[176:179], v[192:195], v[118:121]
	v_mfma_f32_16x16x32_bf16 v[118:121], v[180:183], v[196:199], v[118:121]
	s_addc_u32 s99, s75, 0
	v_mfma_f32_16x16x32_bf16 v[102:105], v[176:179], v[200:203], v[102:105]
	v_mfma_f32_16x16x32_bf16 v[102:105], v[180:183], v[204:207], v[102:105]
	s_add_u32 s100, s76, 0x100000
	v_mfma_f32_16x16x32_bf16 v[86:89], v[176:179], v[208:211], v[86:89]
	v_mfma_f32_16x16x32_bf16 v[86:89], v[180:183], v[212:215], v[86:89]
	s_addc_u32 s101, s77, 0
	v_mfma_f32_16x16x32_bf16 v[70:73], v[176:179], v[216:219], v[70:73]
	v_mfma_f32_16x16x32_bf16 v[70:73], v[180:183], v[220:223], v[70:73]
	v_mfma_f32_16x16x32_bf16 v[114:117], v[184:187], v[192:195], v[114:117]
	v_mfma_f32_16x16x32_bf16 v[114:117], v[188:191], v[196:199], v[114:117]
	v_mfma_f32_16x16x32_bf16 v[98:101], v[184:187], v[200:203], v[98:101]
	v_mfma_f32_16x16x32_bf16 v[98:101], v[188:191], v[204:207], v[98:101]
	v_mfma_f32_16x16x32_bf16 v[82:85], v[184:187], v[208:211], v[82:85]
	v_mfma_f32_16x16x32_bf16 v[82:85], v[188:191], v[212:215], v[82:85]
	v_mfma_f32_16x16x32_bf16 v[66:69], v[184:187], v[216:219], v[66:69]
	v_mfma_f32_16x16x32_bf16 v[66:69], v[188:191], v[220:223], v[66:69]
	s_setprio 0
	s_barrier
	s_add_i32 m0, s33, 0x10000
	ds_read_b128 v[192:195], v163 offset:16384
	global_load_lds_dwordx4 v134, s[74:75]
	s_add_i32 m0, s33, 0x12000
	ds_read_b128 v[196:199], v163 offset:17408
	global_load_lds_dwordx4 v130, s[74:75]
	s_add_i32 m0, s33, 0x14000
	ds_read_b128 v[200:203], v163 offset:18432
	global_load_lds_dwordx4 v134, s[98:99]
	s_add_i32 m0, s33, 0x16000
	ds_read_b128 v[204:207], v163 offset:19456
	global_load_lds_dwordx4 v130, s[98:99]
	s_mov_b32 m0, s33
	ds_read_b128 v[208:211], v163 offset:20480
	global_load_lds_dwordx4 v136, s[76:77]
	s_add_i32 m0, s33, 0x2000
	ds_read_b128 v[212:215], v163 offset:21504
	global_load_lds_dwordx4 v132, s[76:77]
	ds_read_b128 v[216:219], v163 offset:22528
	ds_read_b128 v[220:223], v163 offset:23552
	s_waitcnt vmcnt(8) lgkmcnt(0)
	s_barrier
	s_setprio 1
	v_mfma_f32_16x16x32_bf16 v[62:65], v[154:157], v[192:195], v[62:65]
	v_mfma_f32_16x16x32_bf16 v[62:65], v[164:167], v[196:199], v[62:65]
	v_mfma_f32_16x16x32_bf16 v[46:49], v[154:157], v[200:203], v[46:49]
	v_mfma_f32_16x16x32_bf16 v[46:49], v[164:167], v[204:207], v[46:49]
	v_mfma_f32_16x16x32_bf16 v[30:33], v[154:157], v[208:211], v[30:33]
	v_mfma_f32_16x16x32_bf16 v[30:33], v[164:167], v[212:215], v[30:33]
	v_mfma_f32_16x16x32_bf16 v[14:17], v[154:157], v[216:219], v[14:17]
	v_mfma_f32_16x16x32_bf16 v[14:17], v[164:167], v[220:223], v[14:17]
	v_mfma_f32_16x16x32_bf16 v[58:61], v[168:171], v[192:195], v[58:61]
	v_mfma_f32_16x16x32_bf16 v[58:61], v[172:175], v[196:199], v[58:61]
	v_mfma_f32_16x16x32_bf16 v[42:45], v[168:171], v[200:203], v[42:45]
	v_mfma_f32_16x16x32_bf16 v[42:45], v[172:175], v[204:207], v[42:45]
	v_mfma_f32_16x16x32_bf16 v[26:29], v[168:171], v[208:211], v[26:29]
	v_mfma_f32_16x16x32_bf16 v[26:29], v[172:175], v[212:215], v[26:29]
	v_mfma_f32_16x16x32_bf16 v[10:13], v[168:171], v[216:219], v[10:13]
	v_mfma_f32_16x16x32_bf16 v[10:13], v[172:175], v[220:223], v[10:13]
	v_mfma_f32_16x16x32_bf16 v[54:57], v[176:179], v[192:195], v[54:57]
	v_mfma_f32_16x16x32_bf16 v[54:57], v[180:183], v[196:199], v[54:57]
	v_mfma_f32_16x16x32_bf16 v[38:41], v[176:179], v[200:203], v[38:41]
	v_mfma_f32_16x16x32_bf16 v[38:41], v[180:183], v[204:207], v[38:41]
	v_mfma_f32_16x16x32_bf16 v[22:25], v[176:179], v[208:211], v[22:25]
	v_mfma_f32_16x16x32_bf16 v[22:25], v[180:183], v[212:215], v[22:25]
	v_mfma_f32_16x16x32_bf16 v[6:9], v[176:179], v[216:219], v[6:9]
	v_mfma_f32_16x16x32_bf16 v[6:9], v[180:183], v[220:223], v[6:9]
	v_mfma_f32_16x16x32_bf16 v[50:53], v[184:187], v[192:195], v[50:53]
	v_mfma_f32_16x16x32_bf16 v[50:53], v[188:191], v[196:199], v[50:53]
	v_mfma_f32_16x16x32_bf16 v[34:37], v[184:187], v[200:203], v[34:37]
	v_mfma_f32_16x16x32_bf16 v[34:37], v[188:191], v[204:207], v[34:37]
	v_mfma_f32_16x16x32_bf16 v[18:21], v[184:187], v[208:211], v[18:21]
	v_mfma_f32_16x16x32_bf16 v[18:21], v[188:191], v[212:215], v[18:21]
	v_mfma_f32_16x16x32_bf16 v[2:5], v[184:187], v[216:219], v[2:5]
	v_mfma_f32_16x16x32_bf16 v[2:5], v[188:191], v[220:223], v[2:5]
	s_setprio 0
	s_barrier
	s_add_i32 m0, s33, 0x4000
	ds_read_b128 v[154:157], v226
	global_load_lds_dwordx4 v136, s[100:101]
	s_add_i32 m0, s33, 0x6000
	ds_read_b128 v[164:167], v226 offset:1024
	global_load_lds_dwordx4 v132, s[100:101]
	ds_read_b128 v[168:171], v226 offset:2048
	ds_read_b128 v[172:175], v226 offset:3072
	ds_read_b128 v[176:179], v227
	ds_read_b128 v[180:183], v227 offset:1024
	ds_read_b128 v[184:187], v227 offset:2048
	ds_read_b128 v[188:191], v227 offset:3072
	ds_read_b128 v[192:195], v163 offset:32768
	ds_read_b128 v[196:199], v163 offset:33792
	ds_read_b128 v[200:203], v163 offset:34816
	ds_read_b128 v[204:207], v163 offset:35840
	ds_read_b128 v[208:211], v163 offset:36864
	ds_read_b128 v[212:215], v163 offset:37888
	ds_read_b128 v[216:219], v163 offset:38912
	ds_read_b128 v[220:223], v163 offset:39936
	s_waitcnt vmcnt(8) lgkmcnt(0)
	s_barrier
	s_setprio 1
	v_mfma_f32_16x16x32_bf16 v[126:129], v[154:157], v[192:195], v[126:129]
	v_mfma_f32_16x16x32_bf16 v[126:129], v[164:167], v[196:199], v[126:129]
	v_mfma_f32_16x16x32_bf16 v[110:113], v[154:157], v[200:203], v[110:113]
	v_mfma_f32_16x16x32_bf16 v[110:113], v[164:167], v[204:207], v[110:113]
	v_mfma_f32_16x16x32_bf16 v[94:97], v[154:157], v[208:211], v[94:97]
	v_mfma_f32_16x16x32_bf16 v[94:97], v[164:167], v[212:215], v[94:97]
	v_mfma_f32_16x16x32_bf16 v[78:81], v[154:157], v[216:219], v[78:81]
	v_mfma_f32_16x16x32_bf16 v[78:81], v[164:167], v[220:223], v[78:81]
	v_mfma_f32_16x16x32_bf16 v[122:125], v[168:171], v[192:195], v[122:125]
	v_mfma_f32_16x16x32_bf16 v[122:125], v[172:175], v[196:199], v[122:125]
	v_mfma_f32_16x16x32_bf16 v[106:109], v[168:171], v[200:203], v[106:109]
	v_mfma_f32_16x16x32_bf16 v[106:109], v[172:175], v[204:207], v[106:109]
	v_mfma_f32_16x16x32_bf16 v[90:93], v[168:171], v[208:211], v[90:93]
	v_mfma_f32_16x16x32_bf16 v[90:93], v[172:175], v[212:215], v[90:93]
	v_mfma_f32_16x16x32_bf16 v[74:77], v[168:171], v[216:219], v[74:77]
	v_mfma_f32_16x16x32_bf16 v[74:77], v[172:175], v[220:223], v[74:77]
	v_mfma_f32_16x16x32_bf16 v[118:121], v[176:179], v[192:195], v[118:121]
	v_mfma_f32_16x16x32_bf16 v[118:121], v[180:183], v[196:199], v[118:121]
	v_mfma_f32_16x16x32_bf16 v[102:105], v[176:179], v[200:203], v[102:105]
	v_mfma_f32_16x16x32_bf16 v[102:105], v[180:183], v[204:207], v[102:105]
	v_mfma_f32_16x16x32_bf16 v[86:89], v[176:179], v[208:211], v[86:89]
	v_mfma_f32_16x16x32_bf16 v[86:89], v[180:183], v[212:215], v[86:89]
	v_mfma_f32_16x16x32_bf16 v[70:73], v[176:179], v[216:219], v[70:73]
	v_mfma_f32_16x16x32_bf16 v[70:73], v[180:183], v[220:223], v[70:73]
	v_mfma_f32_16x16x32_bf16 v[114:117], v[184:187], v[192:195], v[114:117]
	v_mfma_f32_16x16x32_bf16 v[114:117], v[188:191], v[196:199], v[114:117]
	v_mfma_f32_16x16x32_bf16 v[98:101], v[184:187], v[200:203], v[98:101]
	v_mfma_f32_16x16x32_bf16 v[98:101], v[188:191], v[204:207], v[98:101]
	v_mfma_f32_16x16x32_bf16 v[82:85], v[184:187], v[208:211], v[82:85]
	v_mfma_f32_16x16x32_bf16 v[82:85], v[188:191], v[212:215], v[82:85]
	v_mfma_f32_16x16x32_bf16 v[66:69], v[184:187], v[216:219], v[66:69]
	v_mfma_f32_16x16x32_bf16 v[66:69], v[188:191], v[220:223], v[66:69]
	s_setprio 0
	s_barrier
	s_add_i32 m0, s33, 0x17f80
	ds_read_b128 v[192:195], v163 offset:49152
	global_load_lds_dwordx4 v134, s[74:75] offset:128
	s_add_i32 m0, s33, 0x19f80
	ds_read_b128 v[196:199], v163 offset:50176
	global_load_lds_dwordx4 v130, s[74:75] offset:128
	s_add_i32 m0, s33, 0x1bf80
	ds_read_b128 v[200:203], v163 offset:51200
	global_load_lds_dwordx4 v134, s[98:99] offset:128
	s_add_i32 m0, s33, 0x1df80
	ds_read_b128 v[204:207], v163 offset:52224
	global_load_lds_dwordx4 v130, s[98:99] offset:128
	s_add_i32 m0, s33, 0x7f80
	ds_read_b128 v[208:211], v163 offset:53248
	global_load_lds_dwordx4 v136, s[76:77] offset:128
	s_add_i32 m0, s33, 0x9f80
	ds_read_b128 v[212:215], v163 offset:54272
	global_load_lds_dwordx4 v132, s[76:77] offset:128
	ds_read_b128 v[216:219], v163 offset:55296
	ds_read_b128 v[220:223], v163 offset:56320
	s_waitcnt vmcnt(8) lgkmcnt(0)
	s_barrier
	s_setprio 1
	v_mfma_f32_16x16x32_bf16 v[62:65], v[154:157], v[192:195], v[62:65]
	v_mfma_f32_16x16x32_bf16 v[62:65], v[164:167], v[196:199], v[62:65]
	v_mfma_f32_16x16x32_bf16 v[46:49], v[154:157], v[200:203], v[46:49]
	v_mfma_f32_16x16x32_bf16 v[46:49], v[164:167], v[204:207], v[46:49]
	v_mfma_f32_16x16x32_bf16 v[30:33], v[154:157], v[208:211], v[30:33]
	v_mfma_f32_16x16x32_bf16 v[30:33], v[164:167], v[212:215], v[30:33]
	v_mfma_f32_16x16x32_bf16 v[14:17], v[154:157], v[216:219], v[14:17]
	v_mfma_f32_16x16x32_bf16 v[14:17], v[164:167], v[220:223], v[14:17]
	v_mfma_f32_16x16x32_bf16 v[58:61], v[168:171], v[192:195], v[58:61]
	v_mfma_f32_16x16x32_bf16 v[58:61], v[172:175], v[196:199], v[58:61]
	v_mfma_f32_16x16x32_bf16 v[42:45], v[168:171], v[200:203], v[42:45]
	v_mfma_f32_16x16x32_bf16 v[42:45], v[172:175], v[204:207], v[42:45]
	v_mfma_f32_16x16x32_bf16 v[26:29], v[168:171], v[208:211], v[26:29]
	v_mfma_f32_16x16x32_bf16 v[26:29], v[172:175], v[212:215], v[26:29]
	v_mfma_f32_16x16x32_bf16 v[10:13], v[168:171], v[216:219], v[10:13]
	v_mfma_f32_16x16x32_bf16 v[10:13], v[172:175], v[220:223], v[10:13]
	v_mfma_f32_16x16x32_bf16 v[54:57], v[176:179], v[192:195], v[54:57]
	v_mfma_f32_16x16x32_bf16 v[54:57], v[180:183], v[196:199], v[54:57]
	v_mfma_f32_16x16x32_bf16 v[38:41], v[176:179], v[200:203], v[38:41]
	v_mfma_f32_16x16x32_bf16 v[38:41], v[180:183], v[204:207], v[38:41]
	s_add_i32 s83, s83, 2
	v_mfma_f32_16x16x32_bf16 v[22:25], v[176:179], v[208:211], v[22:25]
	v_mfma_f32_16x16x32_bf16 v[22:25], v[180:183], v[212:215], v[22:25]
	s_add_u32 s72, s72, 0x100
	v_mfma_f32_16x16x32_bf16 v[6:9], v[176:179], v[216:219], v[6:9]
	v_mfma_f32_16x16x32_bf16 v[6:9], v[180:183], v[220:223], v[6:9]
	s_addc_u32 s73, s73, 0
	v_mfma_f32_16x16x32_bf16 v[50:53], v[184:187], v[192:195], v[50:53]
	v_mfma_f32_16x16x32_bf16 v[50:53], v[188:191], v[196:199], v[50:53]
	s_add_u32 s81, s81, 0x100
	v_mfma_f32_16x16x32_bf16 v[34:37], v[184:187], v[200:203], v[34:37]
	v_mfma_f32_16x16x32_bf16 v[34:37], v[188:191], v[204:207], v[34:37]
	s_addc_u32 s82, s82, 0
	v_mfma_f32_16x16x32_bf16 v[18:21], v[184:187], v[208:211], v[18:21]
	v_mfma_f32_16x16x32_bf16 v[18:21], v[188:191], v[212:215], v[18:21]
	s_cmp_gt_u32 s83, 61
	v_mfma_f32_16x16x32_bf16 v[2:5], v[184:187], v[216:219], v[2:5]
	v_mfma_f32_16x16x32_bf16 v[2:5], v[188:191], v[220:223], v[2:5]
	s_setprio 0
	s_barrier
	s_cbranch_scc0 .LBB0_265
	s_and_b64 vcc, exec, s[46:47]
	s_cbranch_vccz .LBB0_268
	s_barrier

.LBB0_510:
	s_add_i32 m0, s1, 0xc000
	ds_read_b128 v[146:149], v152
	global_load_lds_dwordx4 v138, s[52:53]
	s_add_i32 m0, s1, 0xe000
	ds_read_b128 v[156:159], v152 offset:1024
	global_load_lds_dwordx4 v140, s[52:53]
	ds_read_b128 v[160:163], v152 offset:2048
	ds_read_b128 v[164:167], v152 offset:3072
	ds_read_b128 v[168:171], v153
	ds_read_b128 v[172:175], v153 offset:1024
	ds_read_b128 v[176:179], v153 offset:2048
	ds_read_b128 v[180:183], v153 offset:3072
	ds_read_b128 v[184:187], v154
	ds_read_b128 v[188:191], v154 offset:1024
	ds_read_b128 v[192:195], v154 offset:2048
	ds_read_b128 v[196:199], v154 offset:3072
	ds_read_b128 v[206:209], v154 offset:4096
	ds_read_b128 v[210:213], v154 offset:5120
	ds_read_b128 v[214:217], v154 offset:6144
	ds_read_b128 v[218:221], v154 offset:7168
	s_waitcnt vmcnt(8) lgkmcnt(0)
	s_barrier
	s_setprio 1
	v_mfma_f32_16x16x32_bf16 v[126:129], v[146:149], v[184:187], v[126:129]
	v_mfma_f32_16x16x32_bf16 v[126:129], v[156:159], v[188:191], v[126:129]
	s_add_u32 s34, s52, 0xfff00080
	v_mfma_f32_16x16x32_bf16 v[110:113], v[146:149], v[192:195], v[110:113]
	v_mfma_f32_16x16x32_bf16 v[110:113], v[156:159], v[196:199], v[110:113]
	s_addc_u32 s36, s53, -1
	v_mfma_f32_16x16x32_bf16 v[94:97], v[146:149], v[206:209], v[94:97]
	v_mfma_f32_16x16x32_bf16 v[94:97], v[156:159], v[210:213], v[94:97]
	s_cmp_eq_u32 s62, 60
	v_mfma_f32_16x16x32_bf16 v[78:81], v[146:149], v[214:217], v[78:81]
	v_mfma_f32_16x16x32_bf16 v[78:81], v[156:159], v[218:221], v[78:81]
	s_cselect_b32 s67, s45, s36
	v_mfma_f32_16x16x32_bf16 v[122:125], v[160:163], v[184:187], v[122:125]
	v_mfma_f32_16x16x32_bf16 v[122:125], v[164:167], v[188:191], v[122:125]
	s_cselect_b32 s66, s51, s34
	v_mfma_f32_16x16x32_bf16 v[106:109], v[160:163], v[192:195], v[106:109]
	v_mfma_f32_16x16x32_bf16 v[106:109], v[164:167], v[196:199], v[106:109]
	s_cselect_b32 s55, s23, s61
	v_mfma_f32_16x16x32_bf16 v[90:93], v[160:163], v[206:209], v[90:93]
	v_mfma_f32_16x16x32_bf16 v[90:93], v[164:167], v[210:213], v[90:93]
	s_cselect_b32 s54, s59, s60
	v_mfma_f32_16x16x32_bf16 v[74:77], v[160:163], v[214:217], v[74:77]
	v_mfma_f32_16x16x32_bf16 v[74:77], v[164:167], v[218:221], v[74:77]
	s_add_u32 s98, s54, 0x100000
	v_mfma_f32_16x16x32_bf16 v[118:121], v[168:171], v[184:187], v[118:121]
	v_mfma_f32_16x16x32_bf16 v[118:121], v[172:175], v[188:191], v[118:121]
	s_addc_u32 s99, s55, 0
	v_mfma_f32_16x16x32_bf16 v[102:105], v[168:171], v[192:195], v[102:105]
	v_mfma_f32_16x16x32_bf16 v[102:105], v[172:175], v[196:199], v[102:105]
	s_add_u32 s100, s66, 0x100000
	v_mfma_f32_16x16x32_bf16 v[86:89], v[168:171], v[206:209], v[86:89]
	v_mfma_f32_16x16x32_bf16 v[86:89], v[172:175], v[210:213], v[86:89]
	s_addc_u32 s101, s67, 0
	v_mfma_f32_16x16x32_bf16 v[70:73], v[168:171], v[214:217], v[70:73]
	v_mfma_f32_16x16x32_bf16 v[70:73], v[172:175], v[218:221], v[70:73]
	v_mfma_f32_16x16x32_bf16 v[114:117], v[176:179], v[184:187], v[114:117]
	v_mfma_f32_16x16x32_bf16 v[114:117], v[180:183], v[188:191], v[114:117]
	v_mfma_f32_16x16x32_bf16 v[98:101], v[176:179], v[192:195], v[98:101]
	v_mfma_f32_16x16x32_bf16 v[98:101], v[180:183], v[196:199], v[98:101]
	v_mfma_f32_16x16x32_bf16 v[82:85], v[176:179], v[206:209], v[82:85]
	v_mfma_f32_16x16x32_bf16 v[82:85], v[180:183], v[210:213], v[82:85]
	v_mfma_f32_16x16x32_bf16 v[66:69], v[176:179], v[214:217], v[66:69]
	v_mfma_f32_16x16x32_bf16 v[66:69], v[180:183], v[218:221], v[66:69]
	s_setprio 0
	s_barrier
	s_add_i32 m0, s1, 0x10000
	ds_read_b128 v[184:187], v154 offset:16384
	global_load_lds_dwordx4 v132, s[54:55]
	s_add_i32 m0, s1, 0x12000
	ds_read_b128 v[188:191], v154 offset:17408
	global_load_lds_dwordx4 v136, s[54:55]
	s_add_i32 m0, s1, 0x14000
	ds_read_b128 v[192:195], v154 offset:18432
	global_load_lds_dwordx4 v132, s[98:99]
	s_add_i32 m0, s1, 0x16000
	ds_read_b128 v[196:199], v154 offset:19456
	global_load_lds_dwordx4 v136, s[98:99]
	s_mov_b32 m0, s1
	ds_read_b128 v[206:209], v154 offset:20480
	global_load_lds_dwordx4 v130, s[66:67]
	s_add_i32 m0, s1, 0x2000
	ds_read_b128 v[210:213], v154 offset:21504
	global_load_lds_dwordx4 v134, s[66:67]
	ds_read_b128 v[214:217], v154 offset:22528
	ds_read_b128 v[218:221], v154 offset:23552
	s_waitcnt vmcnt(8) lgkmcnt(0)
	s_barrier
	s_setprio 1
	v_mfma_f32_16x16x32_bf16 v[62:65], v[146:149], v[184:187], v[62:65]
	v_mfma_f32_16x16x32_bf16 v[62:65], v[156:159], v[188:191], v[62:65]
	v_mfma_f32_16x16x32_bf16 v[46:49], v[146:149], v[192:195], v[46:49]
	v_mfma_f32_16x16x32_bf16 v[46:49], v[156:159], v[196:199], v[46:49]
	v_mfma_f32_16x16x32_bf16 v[30:33], v[146:149], v[206:209], v[30:33]
	v_mfma_f32_16x16x32_bf16 v[30:33], v[156:159], v[210:213], v[30:33]
	v_mfma_f32_16x16x32_bf16 v[14:17], v[146:149], v[214:217], v[14:17]
	v_mfma_f32_16x16x32_bf16 v[14:17], v[156:159], v[218:221], v[14:17]
	v_mfma_f32_16x16x32_bf16 v[58:61], v[160:163], v[184:187], v[58:61]
	v_mfma_f32_16x16x32_bf16 v[58:61], v[164:167], v[188:191], v[58:61]
	v_mfma_f32_16x16x32_bf16 v[42:45], v[160:163], v[192:195], v[42:45]
	v_mfma_f32_16x16x32_bf16 v[42:45], v[164:167], v[196:199], v[42:45]
	v_mfma_f32_16x16x32_bf16 v[26:29], v[160:163], v[206:209], v[26:29]
	v_mfma_f32_16x16x32_bf16 v[26:29], v[164:167], v[210:213], v[26:29]
	v_mfma_f32_16x16x32_bf16 v[10:13], v[160:163], v[214:217], v[10:13]
	v_mfma_f32_16x16x32_bf16 v[10:13], v[164:167], v[218:221], v[10:13]
	v_mfma_f32_16x16x32_bf16 v[54:57], v[168:171], v[184:187], v[54:57]
	v_mfma_f32_16x16x32_bf16 v[54:57], v[172:175], v[188:191], v[54:57]
	v_mfma_f32_16x16x32_bf16 v[38:41], v[168:171], v[192:195], v[38:41]
	v_mfma_f32_16x16x32_bf16 v[38:41], v[172:175], v[196:199], v[38:41]
	v_mfma_f32_16x16x32_bf16 v[22:25], v[168:171], v[206:209], v[22:25]
	v_mfma_f32_16x16x32_bf16 v[22:25], v[172:175], v[210:213], v[22:25]
	v_mfma_f32_16x16x32_bf16 v[6:9], v[168:171], v[214:217], v[6:9]
	v_mfma_f32_16x16x32_bf16 v[6:9], v[172:175], v[218:221], v[6:9]
	v_mfma_f32_16x16x32_bf16 v[50:53], v[176:179], v[184:187], v[50:53]
	v_mfma_f32_16x16x32_bf16 v[50:53], v[180:183], v[188:191], v[50:53]
	v_mfma_f32_16x16x32_bf16 v[34:37], v[176:179], v[192:195], v[34:37]
	v_mfma_f32_16x16x32_bf16 v[34:37], v[180:183], v[196:199], v[34:37]
	v_mfma_f32_16x16x32_bf16 v[18:21], v[176:179], v[206:209], v[18:21]
	v_mfma_f32_16x16x32_bf16 v[18:21], v[180:183], v[210:213], v[18:21]
	v_mfma_f32_16x16x32_bf16 v[2:5], v[176:179], v[214:217], v[2:5]
	v_mfma_f32_16x16x32_bf16 v[2:5], v[180:183], v[218:221], v[2:5]
	s_setprio 0
	s_barrier
	s_add_i32 m0, s1, 0x4000
	ds_read_b128 v[146:149], v226
	global_load_lds_dwordx4 v130, s[100:101]
	s_add_i32 m0, s1, 0x6000
	ds_read_b128 v[156:159], v226 offset:1024
	global_load_lds_dwordx4 v134, s[100:101]
	ds_read_b128 v[160:163], v226 offset:2048
	ds_read_b128 v[164:167], v226 offset:3072
	ds_read_b128 v[168:171], v227
	ds_read_b128 v[172:175], v227 offset:1024
	ds_read_b128 v[176:179], v227 offset:2048
	ds_read_b128 v[180:183], v227 offset:3072
	ds_read_b128 v[184:187], v154 offset:32768
	ds_read_b128 v[188:191], v154 offset:33792
	ds_read_b128 v[192:195], v154 offset:34816
	ds_read_b128 v[196:199], v154 offset:35840
	ds_read_b128 v[206:209], v154 offset:36864
	ds_read_b128 v[210:213], v154 offset:37888
	ds_read_b128 v[214:217], v154 offset:38912
	ds_read_b128 v[218:221], v154 offset:39936
	s_waitcnt vmcnt(8) lgkmcnt(0)
	s_barrier
	s_setprio 1
	v_mfma_f32_16x16x32_bf16 v[126:129], v[146:149], v[184:187], v[126:129]
	v_mfma_f32_16x16x32_bf16 v[126:129], v[156:159], v[188:191], v[126:129]
	v_mfma_f32_16x16x32_bf16 v[110:113], v[146:149], v[192:195], v[110:113]
	v_mfma_f32_16x16x32_bf16 v[110:113], v[156:159], v[196:199], v[110:113]
	v_mfma_f32_16x16x32_bf16 v[94:97], v[146:149], v[206:209], v[94:97]
	v_mfma_f32_16x16x32_bf16 v[94:97], v[156:159], v[210:213], v[94:97]
	v_mfma_f32_16x16x32_bf16 v[78:81], v[146:149], v[214:217], v[78:81]
	v_mfma_f32_16x16x32_bf16 v[78:81], v[156:159], v[218:221], v[78:81]
	v_mfma_f32_16x16x32_bf16 v[122:125], v[160:163], v[184:187], v[122:125]
	v_mfma_f32_16x16x32_bf16 v[122:125], v[164:167], v[188:191], v[122:125]
	v_mfma_f32_16x16x32_bf16 v[106:109], v[160:163], v[192:195], v[106:109]
	v_mfma_f32_16x16x32_bf16 v[106:109], v[164:167], v[196:199], v[106:109]
	v_mfma_f32_16x16x32_bf16 v[90:93], v[160:163], v[206:209], v[90:93]
	v_mfma_f32_16x16x32_bf16 v[90:93], v[164:167], v[210:213], v[90:93]
	v_mfma_f32_16x16x32_bf16 v[74:77], v[160:163], v[214:217], v[74:77]
	v_mfma_f32_16x16x32_bf16 v[74:77], v[164:167], v[218:221], v[74:77]
	v_mfma_f32_16x16x32_bf16 v[118:121], v[168:171], v[184:187], v[118:121]
	v_mfma_f32_16x16x32_bf16 v[118:121], v[172:175], v[188:191], v[118:121]
	v_mfma_f32_16x16x32_bf16 v[102:105], v[168:171], v[192:195], v[102:105]
	v_mfma_f32_16x16x32_bf16 v[102:105], v[172:175], v[196:199], v[102:105]
	v_mfma_f32_16x16x32_bf16 v[86:89], v[168:171], v[206:209], v[86:89]
	v_mfma_f32_16x16x32_bf16 v[86:89], v[172:175], v[210:213], v[86:89]
	v_mfma_f32_16x16x32_bf16 v[70:73], v[168:171], v[214:217], v[70:73]
	v_mfma_f32_16x16x32_bf16 v[70:73], v[172:175], v[218:221], v[70:73]
	v_mfma_f32_16x16x32_bf16 v[114:117], v[176:179], v[184:187], v[114:117]
	v_mfma_f32_16x16x32_bf16 v[114:117], v[180:183], v[188:191], v[114:117]
	v_mfma_f32_16x16x32_bf16 v[98:101], v[176:179], v[192:195], v[98:101]
	v_mfma_f32_16x16x32_bf16 v[98:101], v[180:183], v[196:199], v[98:101]
	v_mfma_f32_16x16x32_bf16 v[82:85], v[176:179], v[206:209], v[82:85]
	v_mfma_f32_16x16x32_bf16 v[82:85], v[180:183], v[210:213], v[82:85]
	v_mfma_f32_16x16x32_bf16 v[66:69], v[176:179], v[214:217], v[66:69]
	v_mfma_f32_16x16x32_bf16 v[66:69], v[180:183], v[218:221], v[66:69]
	s_setprio 0
	s_barrier
	s_add_i32 m0, s1, 0x17f80
	ds_read_b128 v[184:187], v154 offset:49152
	global_load_lds_dwordx4 v132, s[54:55] offset:128
	s_add_i32 m0, s1, 0x19f80
	ds_read_b128 v[188:191], v154 offset:50176
	global_load_lds_dwordx4 v136, s[54:55] offset:128
	s_add_i32 m0, s1, 0x1bf80
	ds_read_b128 v[192:195], v154 offset:51200
	global_load_lds_dwordx4 v132, s[98:99] offset:128
	s_add_i32 m0, s1, 0x1df80
	ds_read_b128 v[196:199], v154 offset:52224
	global_load_lds_dwordx4 v136, s[98:99] offset:128
	s_add_i32 m0, s1, 0x7f80
	ds_read_b128 v[206:209], v154 offset:53248
	global_load_lds_dwordx4 v130, s[66:67] offset:128
	s_add_i32 m0, s1, 0x9f80
	ds_read_b128 v[210:213], v154 offset:54272
	global_load_lds_dwordx4 v134, s[66:67] offset:128
	ds_read_b128 v[214:217], v154 offset:55296
	ds_read_b128 v[218:221], v154 offset:56320
	s_waitcnt vmcnt(8) lgkmcnt(0)
	s_barrier
	s_setprio 1
	v_mfma_f32_16x16x32_bf16 v[62:65], v[146:149], v[184:187], v[62:65]
	v_mfma_f32_16x16x32_bf16 v[62:65], v[156:159], v[188:191], v[62:65]
	v_mfma_f32_16x16x32_bf16 v[46:49], v[146:149], v[192:195], v[46:49]
	v_mfma_f32_16x16x32_bf16 v[46:49], v[156:159], v[196:199], v[46:49]
	v_mfma_f32_16x16x32_bf16 v[30:33], v[146:149], v[206:209], v[30:33]
	v_mfma_f32_16x16x32_bf16 v[30:33], v[156:159], v[210:213], v[30:33]
	v_mfma_f32_16x16x32_bf16 v[14:17], v[146:149], v[214:217], v[14:17]
	v_mfma_f32_16x16x32_bf16 v[14:17], v[156:159], v[218:221], v[14:17]
	v_mfma_f32_16x16x32_bf16 v[58:61], v[160:163], v[184:187], v[58:61]
	v_mfma_f32_16x16x32_bf16 v[58:61], v[164:167], v[188:191], v[58:61]
	v_mfma_f32_16x16x32_bf16 v[42:45], v[160:163], v[192:195], v[42:45]
	v_mfma_f32_16x16x32_bf16 v[42:45], v[164:167], v[196:199], v[42:45]
	v_mfma_f32_16x16x32_bf16 v[26:29], v[160:163], v[206:209], v[26:29]
	v_mfma_f32_16x16x32_bf16 v[26:29], v[164:167], v[210:213], v[26:29]
	v_mfma_f32_16x16x32_bf16 v[10:13], v[160:163], v[214:217], v[10:13]
	v_mfma_f32_16x16x32_bf16 v[10:13], v[164:167], v[218:221], v[10:13]
	v_mfma_f32_16x16x32_bf16 v[54:57], v[168:171], v[184:187], v[54:57]
	v_mfma_f32_16x16x32_bf16 v[54:57], v[172:175], v[188:191], v[54:57]
	v_mfma_f32_16x16x32_bf16 v[38:41], v[168:171], v[192:195], v[38:41]
	v_mfma_f32_16x16x32_bf16 v[38:41], v[172:175], v[196:199], v[38:41]
	s_add_i32 s62, s62, 2
	v_mfma_f32_16x16x32_bf16 v[22:25], v[168:171], v[206:209], v[22:25]
	v_mfma_f32_16x16x32_bf16 v[22:25], v[172:175], v[210:213], v[22:25]
	s_add_u32 s60, s60, 0x100
	v_mfma_f32_16x16x32_bf16 v[6:9], v[168:171], v[214:217], v[6:9]
	v_mfma_f32_16x16x32_bf16 v[6:9], v[172:175], v[218:221], v[6:9]
	s_addc_u32 s61, s61, 0
	v_mfma_f32_16x16x32_bf16 v[50:53], v[176:179], v[184:187], v[50:53]
	v_mfma_f32_16x16x32_bf16 v[50:53], v[180:183], v[188:191], v[50:53]
	s_add_u32 s52, s52, 0x100
	v_mfma_f32_16x16x32_bf16 v[34:37], v[176:179], v[192:195], v[34:37]
	v_mfma_f32_16x16x32_bf16 v[34:37], v[180:183], v[196:199], v[34:37]
	s_addc_u32 s53, s53, 0
	v_mfma_f32_16x16x32_bf16 v[18:21], v[176:179], v[206:209], v[18:21]
	v_mfma_f32_16x16x32_bf16 v[18:21], v[180:183], v[210:213], v[18:21]
	s_cmp_gt_u32 s62, 61
	v_mfma_f32_16x16x32_bf16 v[2:5], v[176:179], v[214:217], v[2:5]
	v_mfma_f32_16x16x32_bf16 v[2:5], v[180:183], v[218:221], v[2:5]
	s_setprio 0
	s_barrier
	s_cbranch_scc0 .LBB0_510
	s_and_b64 vcc, exec, s[20:21]
	s_cbranch_vccz .LBB0_513
	s_barrier

.LBB0_651:
	s_add_i32 m0, s39, 0xc000
	ds_read_b128 v[130:133], v210
	global_load_lds_dwordx4 v180, s[88:89]
	s_add_i32 m0, s39, 0xe000
	ds_read_b128 v[134:137], v210 offset:1024
	global_load_lds_dwordx4 v182, s[88:89]
	ds_read_b128 v[138:141], v210 offset:2048
	ds_read_b128 v[142:145], v210 offset:3072
	ds_read_b128 v[146:149], v211
	ds_read_b128 v[150:153], v211 offset:1024
	ds_read_b128 v[154:157], v211 offset:2048
	ds_read_b128 v[158:161], v211 offset:3072
	ds_read_b128 v[162:165], v212
	ds_read_b128 v[166:169], v212 offset:1024
	ds_read_b128 v[188:191], v212 offset:2048
	ds_read_b128 v[192:195], v212 offset:3072
	ds_read_b128 v[196:199], v212 offset:4096
	ds_read_b128 v[214:217], v212 offset:5120
	ds_read_b128 v[218:221], v212 offset:6144
	ds_read_b128 v[222:225], v212 offset:7168
	s_waitcnt vmcnt(8) lgkmcnt(0)
	s_barrier
	s_setprio 1
	v_mfma_f32_16x16x32_bf16 v[126:129], v[130:133], v[162:165], v[126:129]
	v_mfma_f32_16x16x32_bf16 v[126:129], v[134:137], v[166:169], v[126:129]
	s_add_u32 s90, s88, 0x100
	v_mfma_f32_16x16x32_bf16 v[122:125], v[130:133], v[188:191], v[122:125]
	v_mfma_f32_16x16x32_bf16 v[122:125], v[134:137], v[192:195], v[122:125]
	s_addc_u32 s91, s89, 0
	v_mfma_f32_16x16x32_bf16 v[110:113], v[130:133], v[196:199], v[110:113]
	v_mfma_f32_16x16x32_bf16 v[110:113], v[134:137], v[214:217], v[110:113]
	s_cmp_eq_u32 s66, 60
	v_mfma_f32_16x16x32_bf16 v[106:109], v[130:133], v[218:221], v[106:109]
	v_mfma_f32_16x16x32_bf16 v[106:109], v[134:137], v[222:225], v[106:109]
	s_cselect_b32 s95, s79, s91
	v_mfma_f32_16x16x32_bf16 v[62:65], v[138:141], v[162:165], v[62:65]
	v_mfma_f32_16x16x32_bf16 v[62:65], v[142:145], v[166:169], v[62:65]
	s_cselect_b32 s94, s85, s90
	v_mfma_f32_16x16x32_bf16 v[58:61], v[138:141], v[188:191], v[58:61]
	v_mfma_f32_16x16x32_bf16 v[58:61], v[142:145], v[192:195], v[58:61]
	s_cselect_b32 s93, s77, vcc_hi
	v_mfma_f32_16x16x32_bf16 v[50:53], v[138:141], v[196:199], v[50:53]
	v_mfma_f32_16x16x32_bf16 v[50:53], v[142:145], v[214:217], v[50:53]
	s_cselect_b32 s92, s87, vcc_lo
	v_mfma_f32_16x16x32_bf16 v[42:45], v[138:141], v[218:221], v[42:45]
	v_mfma_f32_16x16x32_bf16 v[42:45], v[142:145], v[222:225], v[42:45]
	s_add_u32 s98, s92, 0x100000
	v_mfma_f32_16x16x32_bf16 v[118:121], v[146:149], v[162:165], v[118:121]
	v_mfma_f32_16x16x32_bf16 v[118:121], v[150:153], v[166:169], v[118:121]
	s_addc_u32 s99, s93, 0
	v_mfma_f32_16x16x32_bf16 v[114:117], v[146:149], v[188:191], v[114:117]
	v_mfma_f32_16x16x32_bf16 v[114:117], v[150:153], v[192:195], v[114:117]
	s_add_u32 s100, s94, 0x100000
	v_mfma_f32_16x16x32_bf16 v[102:105], v[146:149], v[196:199], v[102:105]
	v_mfma_f32_16x16x32_bf16 v[102:105], v[150:153], v[214:217], v[102:105]
	s_addc_u32 s101, s95, 0
	v_mfma_f32_16x16x32_bf16 v[98:101], v[146:149], v[218:221], v[98:101]
	v_mfma_f32_16x16x32_bf16 v[98:101], v[150:153], v[222:225], v[98:101]
	v_mfma_f32_16x16x32_bf16 v[54:57], v[154:157], v[162:165], v[54:57]
	v_mfma_f32_16x16x32_bf16 v[54:57], v[158:161], v[166:169], v[54:57]
	v_mfma_f32_16x16x32_bf16 v[46:49], v[154:157], v[188:191], v[46:49]
	v_mfma_f32_16x16x32_bf16 v[46:49], v[158:161], v[192:195], v[46:49]
	v_mfma_f32_16x16x32_bf16 v[38:41], v[154:157], v[196:199], v[38:41]
	v_mfma_f32_16x16x32_bf16 v[38:41], v[158:161], v[214:217], v[38:41]
	v_mfma_f32_16x16x32_bf16 v[34:37], v[154:157], v[218:221], v[34:37]
	v_mfma_f32_16x16x32_bf16 v[34:37], v[158:161], v[222:225], v[34:37]
	s_setprio 0
	s_barrier
	s_add_i32 m0, s39, 0x10000
	ds_read_b128 v[162:165], v212 offset:16384
	global_load_lds_dwordx4 v172, s[92:93]
	s_add_i32 m0, s39, 0x12000
	ds_read_b128 v[166:169], v212 offset:17408
	global_load_lds_dwordx4 v176, s[92:93]
	s_add_i32 m0, s39, 0x14000
	ds_read_b128 v[188:191], v212 offset:18432
	global_load_lds_dwordx4 v172, s[98:99]
	s_add_i32 m0, s39, 0x16000
	ds_read_b128 v[192:195], v212 offset:19456
	global_load_lds_dwordx4 v176, s[98:99]
	s_mov_b32 m0, s39
	ds_read_b128 v[196:199], v212 offset:20480
	global_load_lds_dwordx4 v170, s[94:95]
	s_add_i32 m0, s39, 0x2000
	ds_read_b128 v[214:217], v212 offset:21504
	global_load_lds_dwordx4 v174, s[94:95]
	ds_read_b128 v[218:221], v212 offset:22528
	ds_read_b128 v[222:225], v212 offset:23552
	s_waitcnt vmcnt(8) lgkmcnt(0)
	s_barrier
	s_setprio 1
	v_mfma_f32_16x16x32_bf16 v[94:97], v[130:133], v[162:165], v[94:97]
	v_mfma_f32_16x16x32_bf16 v[94:97], v[134:137], v[166:169], v[94:97]
	v_mfma_f32_16x16x32_bf16 v[90:93], v[130:133], v[188:191], v[90:93]
	v_mfma_f32_16x16x32_bf16 v[90:93], v[134:137], v[192:195], v[90:93]
	v_mfma_f32_16x16x32_bf16 v[82:85], v[130:133], v[196:199], v[82:85]
	v_mfma_f32_16x16x32_bf16 v[82:85], v[134:137], v[214:217], v[82:85]
	v_mfma_f32_16x16x32_bf16 v[74:77], v[130:133], v[218:221], v[74:77]
	v_mfma_f32_16x16x32_bf16 v[74:77], v[134:137], v[222:225], v[74:77]
	v_mfma_f32_16x16x32_bf16 v[30:33], v[138:141], v[162:165], v[30:33]
	v_mfma_f32_16x16x32_bf16 v[30:33], v[142:145], v[166:169], v[30:33]
	v_mfma_f32_16x16x32_bf16 v[26:29], v[138:141], v[188:191], v[26:29]
	v_mfma_f32_16x16x32_bf16 v[26:29], v[142:145], v[192:195], v[26:29]
	v_mfma_f32_16x16x32_bf16 v[18:21], v[138:141], v[196:199], v[18:21]
	v_mfma_f32_16x16x32_bf16 v[18:21], v[142:145], v[214:217], v[18:21]
	v_mfma_f32_16x16x32_bf16 v[10:13], v[138:141], v[218:221], v[10:13]
	v_mfma_f32_16x16x32_bf16 v[10:13], v[142:145], v[222:225], v[10:13]
	v_mfma_f32_16x16x32_bf16 v[86:89], v[146:149], v[162:165], v[86:89]
	v_mfma_f32_16x16x32_bf16 v[86:89], v[150:153], v[166:169], v[86:89]
	v_mfma_f32_16x16x32_bf16 v[78:81], v[146:149], v[188:191], v[78:81]
	v_mfma_f32_16x16x32_bf16 v[78:81], v[150:153], v[192:195], v[78:81]
	v_mfma_f32_16x16x32_bf16 v[70:73], v[146:149], v[196:199], v[70:73]
	v_mfma_f32_16x16x32_bf16 v[70:73], v[150:153], v[214:217], v[70:73]
	v_mfma_f32_16x16x32_bf16 v[66:69], v[146:149], v[218:221], v[66:69]
	v_mfma_f32_16x16x32_bf16 v[66:69], v[150:153], v[222:225], v[66:69]
	v_mfma_f32_16x16x32_bf16 v[22:25], v[154:157], v[162:165], v[22:25]
	v_mfma_f32_16x16x32_bf16 v[22:25], v[158:161], v[166:169], v[22:25]
	v_mfma_f32_16x16x32_bf16 v[14:17], v[154:157], v[188:191], v[14:17]
	v_mfma_f32_16x16x32_bf16 v[14:17], v[158:161], v[192:195], v[14:17]
	v_mfma_f32_16x16x32_bf16 v[6:9], v[154:157], v[196:199], v[6:9]
	v_mfma_f32_16x16x32_bf16 v[6:9], v[158:161], v[214:217], v[6:9]
	v_mfma_f32_16x16x32_bf16 v[2:5], v[154:157], v[218:221], v[2:5]
	v_mfma_f32_16x16x32_bf16 v[2:5], v[158:161], v[222:225], v[2:5]
	s_setprio 0
	s_barrier
	s_add_i32 m0, s39, 0x4000
	ds_read_b128 v[130:133], v226
	global_load_lds_dwordx4 v170, s[100:101]
	s_add_i32 m0, s39, 0x6000
	ds_read_b128 v[134:137], v226 offset:1024
	global_load_lds_dwordx4 v174, s[100:101]
	ds_read_b128 v[138:141], v226 offset:2048
	ds_read_b128 v[142:145], v226 offset:3072
	ds_read_b128 v[146:149], v227
	ds_read_b128 v[150:153], v227 offset:1024
	ds_read_b128 v[154:157], v227 offset:2048
	ds_read_b128 v[158:161], v227 offset:3072
	ds_read_b128 v[162:165], v212 offset:32768
	ds_read_b128 v[166:169], v212 offset:33792
	ds_read_b128 v[188:191], v212 offset:34816
	ds_read_b128 v[192:195], v212 offset:35840
	ds_read_b128 v[196:199], v212 offset:36864
	ds_read_b128 v[214:217], v212 offset:37888
	ds_read_b128 v[218:221], v212 offset:38912
	ds_read_b128 v[222:225], v212 offset:39936
	s_waitcnt vmcnt(8) lgkmcnt(0)
	s_barrier
	s_setprio 1
	v_mfma_f32_16x16x32_bf16 v[126:129], v[130:133], v[162:165], v[126:129]
	v_mfma_f32_16x16x32_bf16 v[126:129], v[134:137], v[166:169], v[126:129]
	v_mfma_f32_16x16x32_bf16 v[122:125], v[130:133], v[188:191], v[122:125]
	v_mfma_f32_16x16x32_bf16 v[122:125], v[134:137], v[192:195], v[122:125]
	v_mfma_f32_16x16x32_bf16 v[110:113], v[130:133], v[196:199], v[110:113]
	v_mfma_f32_16x16x32_bf16 v[110:113], v[134:137], v[214:217], v[110:113]
	v_mfma_f32_16x16x32_bf16 v[106:109], v[130:133], v[218:221], v[106:109]
	v_mfma_f32_16x16x32_bf16 v[106:109], v[134:137], v[222:225], v[106:109]
	v_mfma_f32_16x16x32_bf16 v[62:65], v[138:141], v[162:165], v[62:65]
	v_mfma_f32_16x16x32_bf16 v[62:65], v[142:145], v[166:169], v[62:65]
	v_mfma_f32_16x16x32_bf16 v[58:61], v[138:141], v[188:191], v[58:61]
	v_mfma_f32_16x16x32_bf16 v[58:61], v[142:145], v[192:195], v[58:61]
	v_mfma_f32_16x16x32_bf16 v[50:53], v[138:141], v[196:199], v[50:53]
	v_mfma_f32_16x16x32_bf16 v[50:53], v[142:145], v[214:217], v[50:53]
	v_mfma_f32_16x16x32_bf16 v[42:45], v[138:141], v[218:221], v[42:45]
	v_mfma_f32_16x16x32_bf16 v[42:45], v[142:145], v[222:225], v[42:45]
	v_mfma_f32_16x16x32_bf16 v[118:121], v[146:149], v[162:165], v[118:121]
	v_mfma_f32_16x16x32_bf16 v[118:121], v[150:153], v[166:169], v[118:121]
	v_mfma_f32_16x16x32_bf16 v[114:117], v[146:149], v[188:191], v[114:117]
	v_mfma_f32_16x16x32_bf16 v[114:117], v[150:153], v[192:195], v[114:117]
	v_mfma_f32_16x16x32_bf16 v[102:105], v[146:149], v[196:199], v[102:105]
	v_mfma_f32_16x16x32_bf16 v[102:105], v[150:153], v[214:217], v[102:105]
	v_mfma_f32_16x16x32_bf16 v[98:101], v[146:149], v[218:221], v[98:101]
	v_mfma_f32_16x16x32_bf16 v[98:101], v[150:153], v[222:225], v[98:101]
	v_mfma_f32_16x16x32_bf16 v[54:57], v[154:157], v[162:165], v[54:57]
	v_mfma_f32_16x16x32_bf16 v[54:57], v[158:161], v[166:169], v[54:57]
	v_mfma_f32_16x16x32_bf16 v[46:49], v[154:157], v[188:191], v[46:49]
	v_mfma_f32_16x16x32_bf16 v[46:49], v[158:161], v[192:195], v[46:49]
	v_mfma_f32_16x16x32_bf16 v[38:41], v[154:157], v[196:199], v[38:41]
	v_mfma_f32_16x16x32_bf16 v[38:41], v[158:161], v[214:217], v[38:41]
	v_mfma_f32_16x16x32_bf16 v[34:37], v[154:157], v[218:221], v[34:37]
	v_mfma_f32_16x16x32_bf16 v[34:37], v[158:161], v[222:225], v[34:37]
	s_setprio 0
	s_barrier
	s_add_i32 m0, s39, 0x17f80
	ds_read_b128 v[162:165], v212 offset:49152
	global_load_lds_dwordx4 v172, s[92:93] offset:128
	s_add_i32 m0, s39, 0x19f80
	ds_read_b128 v[166:169], v212 offset:50176
	global_load_lds_dwordx4 v176, s[92:93] offset:128
	s_add_i32 m0, s39, 0x1bf80
	ds_read_b128 v[188:191], v212 offset:51200
	global_load_lds_dwordx4 v172, s[98:99] offset:128
	s_add_i32 m0, s39, 0x1df80
	ds_read_b128 v[192:195], v212 offset:52224
	global_load_lds_dwordx4 v176, s[98:99] offset:128
	s_add_i32 m0, s39, 0x7f80
	ds_read_b128 v[196:199], v212 offset:53248
	global_load_lds_dwordx4 v170, s[94:95] offset:128
	s_add_i32 m0, s39, 0x9f80
	ds_read_b128 v[214:217], v212 offset:54272
	global_load_lds_dwordx4 v174, s[94:95] offset:128
	ds_read_b128 v[218:221], v212 offset:55296
	ds_read_b128 v[222:225], v212 offset:56320
	s_waitcnt vmcnt(8) lgkmcnt(0)
	s_barrier
	s_setprio 1
	v_mfma_f32_16x16x32_bf16 v[94:97], v[130:133], v[162:165], v[94:97]
	v_mfma_f32_16x16x32_bf16 v[94:97], v[134:137], v[166:169], v[94:97]
	v_mfma_f32_16x16x32_bf16 v[90:93], v[130:133], v[188:191], v[90:93]
	v_mfma_f32_16x16x32_bf16 v[90:93], v[134:137], v[192:195], v[90:93]
	v_mfma_f32_16x16x32_bf16 v[82:85], v[130:133], v[196:199], v[82:85]
	v_mfma_f32_16x16x32_bf16 v[82:85], v[134:137], v[214:217], v[82:85]
	v_mfma_f32_16x16x32_bf16 v[74:77], v[130:133], v[218:221], v[74:77]
	v_mfma_f32_16x16x32_bf16 v[74:77], v[134:137], v[222:225], v[74:77]
	v_mfma_f32_16x16x32_bf16 v[30:33], v[138:141], v[162:165], v[30:33]
	v_mfma_f32_16x16x32_bf16 v[30:33], v[142:145], v[166:169], v[30:33]
	v_mfma_f32_16x16x32_bf16 v[26:29], v[138:141], v[188:191], v[26:29]
	v_mfma_f32_16x16x32_bf16 v[26:29], v[142:145], v[192:195], v[26:29]
	v_mfma_f32_16x16x32_bf16 v[18:21], v[138:141], v[196:199], v[18:21]
	v_mfma_f32_16x16x32_bf16 v[18:21], v[142:145], v[214:217], v[18:21]
	v_mfma_f32_16x16x32_bf16 v[10:13], v[138:141], v[218:221], v[10:13]
	v_mfma_f32_16x16x32_bf16 v[10:13], v[142:145], v[222:225], v[10:13]
	v_mfma_f32_16x16x32_bf16 v[86:89], v[146:149], v[162:165], v[86:89]
	v_mfma_f32_16x16x32_bf16 v[86:89], v[150:153], v[166:169], v[86:89]
	v_mfma_f32_16x16x32_bf16 v[78:81], v[146:149], v[188:191], v[78:81]
	v_mfma_f32_16x16x32_bf16 v[78:81], v[150:153], v[192:195], v[78:81]
	v_mfma_f32_16x16x32_bf16 v[70:73], v[146:149], v[196:199], v[70:73]
	v_mfma_f32_16x16x32_bf16 v[70:73], v[150:153], v[214:217], v[70:73]
	s_add_i32 s66, s66, 2
	v_mfma_f32_16x16x32_bf16 v[66:69], v[146:149], v[218:221], v[66:69]
	v_mfma_f32_16x16x32_bf16 v[66:69], v[150:153], v[222:225], v[66:69]
	s_add_u32 vcc_lo, vcc_lo, 0x100
	v_mfma_f32_16x16x32_bf16 v[22:25], v[154:157], v[162:165], v[22:25]
	v_mfma_f32_16x16x32_bf16 v[22:25], v[158:161], v[166:169], v[22:25]
	s_addc_u32 vcc_hi, vcc_hi, 0
	v_mfma_f32_16x16x32_bf16 v[14:17], v[154:157], v[188:191], v[14:17]
	v_mfma_f32_16x16x32_bf16 v[14:17], v[158:161], v[192:195], v[14:17]
	s_mov_b64 s[88:89], s[90:91]
	v_mfma_f32_16x16x32_bf16 v[6:9], v[154:157], v[196:199], v[6:9]
	v_mfma_f32_16x16x32_bf16 v[6:9], v[158:161], v[214:217], v[6:9]
	s_cmp_gt_u32 s66, 61
	v_mfma_f32_16x16x32_bf16 v[2:5], v[154:157], v[218:221], v[2:5]
	v_mfma_f32_16x16x32_bf16 v[2:5], v[158:161], v[222:225], v[2:5]
	s_setprio 0
	s_barrier
	s_cbranch_scc0 .LBB0_651
	s_and_b64 vcc, exec, s[36:37]
	s_cbranch_vccz .LBB0_654
	s_barrier

.LBB0_834:
	s_add_i32 m0, s1, 0xc000
	ds_read_b128 v[146:149], v152
	global_load_lds_dwordx4 v138, s[42:43]
	s_add_i32 m0, s1, 0xe000
	ds_read_b128 v[156:159], v152 offset:1024
	global_load_lds_dwordx4 v140, s[42:43]
	ds_read_b128 v[160:163], v152 offset:2048
	ds_read_b128 v[164:167], v152 offset:3072
	ds_read_b128 v[168:171], v153
	ds_read_b128 v[172:175], v153 offset:1024
	ds_read_b128 v[176:179], v153 offset:2048
	ds_read_b128 v[180:183], v153 offset:3072
	ds_read_b128 v[184:187], v154
	ds_read_b128 v[188:191], v154 offset:1024
	ds_read_b128 v[192:195], v154 offset:2048
	ds_read_b128 v[196:199], v154 offset:3072
	ds_read_b128 v[206:209], v154 offset:4096
	ds_read_b128 v[210:213], v154 offset:5120
	ds_read_b128 v[214:217], v154 offset:6144
	ds_read_b128 v[218:221], v154 offset:7168
	s_waitcnt vmcnt(8) lgkmcnt(0)
	s_barrier
	s_setprio 1
	v_mfma_f32_16x16x32_bf16 v[126:129], v[146:149], v[184:187], v[126:129]
	v_mfma_f32_16x16x32_bf16 v[126:129], v[156:159], v[188:191], v[126:129]
	s_add_u32 s34, s42, 0x1fc000
	s_addc_u32 s44, s43, 0
	v_mfma_f32_16x16x32_bf16 v[110:113], v[146:149], v[192:195], v[110:113]
	v_mfma_f32_16x16x32_bf16 v[110:113], v[156:159], v[196:199], v[110:113]
	s_cmpk_eq_i32 s61, 0xa8
	s_cselect_b32 s48, s41, s34
	v_mfma_f32_16x16x32_bf16 v[94:97], v[146:149], v[206:209], v[94:97]
	v_mfma_f32_16x16x32_bf16 v[94:97], v[156:159], v[210:213], v[94:97]
	s_cselect_b32 s49, s23, s44
	s_cselect_b32 s47, s21, s60
	v_mfma_f32_16x16x32_bf16 v[78:81], v[146:149], v[214:217], v[78:81]
	v_mfma_f32_16x16x32_bf16 v[78:81], v[156:159], v[218:221], v[78:81]
	s_cselect_b32 s46, s58, s59
	s_add_u32 s44, s48, 0x200000
	v_mfma_f32_16x16x32_bf16 v[122:125], v[160:163], v[184:187], v[122:125]
	v_mfma_f32_16x16x32_bf16 v[122:125], v[164:167], v[188:191], v[122:125]
	s_addc_u32 s45, s49, 0
	s_add_u32 s62, s46, 0x4000
	v_mfma_f32_16x16x32_bf16 v[106:109], v[160:163], v[192:195], v[106:109]
	v_mfma_f32_16x16x32_bf16 v[106:109], v[164:167], v[196:199], v[106:109]
	s_addc_u32 s63, s47, 0
	s_add_u32 s100, s48, 0x4000
	v_mfma_f32_16x16x32_bf16 v[90:93], v[160:163], v[206:209], v[90:93]
	v_mfma_f32_16x16x32_bf16 v[90:93], v[164:167], v[210:213], v[90:93]
	s_addc_u32 s101, s49, 0
	s_add_u32 s98, s46, 0x80000
	v_mfma_f32_16x16x32_bf16 v[74:77], v[160:163], v[214:217], v[74:77]
	v_mfma_f32_16x16x32_bf16 v[74:77], v[164:167], v[218:221], v[74:77]
	s_addc_u32 s99, s47, 0
	s_add_u32 s24, s46, 0x84000
	v_mfma_f32_16x16x32_bf16 v[118:121], v[168:171], v[184:187], v[118:121]
	v_mfma_f32_16x16x32_bf16 v[118:121], v[172:175], v[188:191], v[118:121]
	s_addc_u32 s25, s47, 0
	v_mfma_f32_16x16x32_bf16 v[102:105], v[168:171], v[192:195], v[102:105]
	v_mfma_f32_16x16x32_bf16 v[102:105], v[172:175], v[196:199], v[102:105]
	v_mfma_f32_16x16x32_bf16 v[86:89], v[168:171], v[206:209], v[86:89]
	v_mfma_f32_16x16x32_bf16 v[86:89], v[172:175], v[210:213], v[86:89]
	v_mfma_f32_16x16x32_bf16 v[70:73], v[168:171], v[214:217], v[70:73]
	v_mfma_f32_16x16x32_bf16 v[70:73], v[172:175], v[218:221], v[70:73]
	v_mfma_f32_16x16x32_bf16 v[114:117], v[176:179], v[184:187], v[114:117]
	v_mfma_f32_16x16x32_bf16 v[114:117], v[180:183], v[188:191], v[114:117]
	v_mfma_f32_16x16x32_bf16 v[98:101], v[176:179], v[192:195], v[98:101]
	v_mfma_f32_16x16x32_bf16 v[98:101], v[180:183], v[196:199], v[98:101]
	v_mfma_f32_16x16x32_bf16 v[82:85], v[176:179], v[206:209], v[82:85]
	v_mfma_f32_16x16x32_bf16 v[82:85], v[180:183], v[210:213], v[82:85]
	v_mfma_f32_16x16x32_bf16 v[66:69], v[176:179], v[214:217], v[66:69]
	v_mfma_f32_16x16x32_bf16 v[66:69], v[180:183], v[218:221], v[66:69]
	s_setprio 0
	s_barrier
	s_add_i32 m0, s1, 0x10000
	ds_read_b128 v[184:187], v154 offset:16384
	global_load_lds_dwordx4 v132, s[46:47]
	s_add_i32 m0, s1, 0x12000
	ds_read_b128 v[188:191], v154 offset:17408
	global_load_lds_dwordx4 v136, s[46:47]
	s_add_i32 m0, s1, 0x14000
	ds_read_b128 v[192:195], v154 offset:18432
	global_load_lds_dwordx4 v132, s[62:63]
	s_add_i32 m0, s1, 0x16000
	ds_read_b128 v[196:199], v154 offset:19456
	global_load_lds_dwordx4 v136, s[62:63]
	s_mov_b32 m0, s1
	ds_read_b128 v[206:209], v154 offset:20480
	global_load_lds_dwordx4 v130, s[48:49]
	s_add_i32 m0, s1, 0x2000
	ds_read_b128 v[210:213], v154 offset:21504
	global_load_lds_dwordx4 v134, s[48:49]
	ds_read_b128 v[214:217], v154 offset:22528
	ds_read_b128 v[218:221], v154 offset:23552
	s_waitcnt vmcnt(8) lgkmcnt(0)
	s_barrier
	s_setprio 1
	v_mfma_f32_16x16x32_bf16 v[62:65], v[146:149], v[184:187], v[62:65]
	v_mfma_f32_16x16x32_bf16 v[62:65], v[156:159], v[188:191], v[62:65]
	v_mfma_f32_16x16x32_bf16 v[46:49], v[146:149], v[192:195], v[46:49]
	v_mfma_f32_16x16x32_bf16 v[46:49], v[156:159], v[196:199], v[46:49]
	v_mfma_f32_16x16x32_bf16 v[30:33], v[146:149], v[206:209], v[30:33]
	v_mfma_f32_16x16x32_bf16 v[30:33], v[156:159], v[210:213], v[30:33]
	v_mfma_f32_16x16x32_bf16 v[14:17], v[146:149], v[214:217], v[14:17]
	v_mfma_f32_16x16x32_bf16 v[14:17], v[156:159], v[218:221], v[14:17]
	v_mfma_f32_16x16x32_bf16 v[58:61], v[160:163], v[184:187], v[58:61]
	v_mfma_f32_16x16x32_bf16 v[58:61], v[164:167], v[188:191], v[58:61]
	v_mfma_f32_16x16x32_bf16 v[42:45], v[160:163], v[192:195], v[42:45]
	v_mfma_f32_16x16x32_bf16 v[42:45], v[164:167], v[196:199], v[42:45]
	v_mfma_f32_16x16x32_bf16 v[26:29], v[160:163], v[206:209], v[26:29]
	v_mfma_f32_16x16x32_bf16 v[26:29], v[164:167], v[210:213], v[26:29]
	v_mfma_f32_16x16x32_bf16 v[10:13], v[160:163], v[214:217], v[10:13]
	v_mfma_f32_16x16x32_bf16 v[10:13], v[164:167], v[218:221], v[10:13]
	v_mfma_f32_16x16x32_bf16 v[54:57], v[168:171], v[184:187], v[54:57]
	v_mfma_f32_16x16x32_bf16 v[54:57], v[172:175], v[188:191], v[54:57]
	v_mfma_f32_16x16x32_bf16 v[38:41], v[168:171], v[192:195], v[38:41]
	v_mfma_f32_16x16x32_bf16 v[38:41], v[172:175], v[196:199], v[38:41]
	v_mfma_f32_16x16x32_bf16 v[22:25], v[168:171], v[206:209], v[22:25]
	v_mfma_f32_16x16x32_bf16 v[22:25], v[172:175], v[210:213], v[22:25]
	v_mfma_f32_16x16x32_bf16 v[6:9], v[168:171], v[214:217], v[6:9]
	v_mfma_f32_16x16x32_bf16 v[6:9], v[172:175], v[218:221], v[6:9]
	v_mfma_f32_16x16x32_bf16 v[50:53], v[176:179], v[184:187], v[50:53]
	v_mfma_f32_16x16x32_bf16 v[50:53], v[180:183], v[188:191], v[50:53]
	v_mfma_f32_16x16x32_bf16 v[34:37], v[176:179], v[192:195], v[34:37]
	v_mfma_f32_16x16x32_bf16 v[34:37], v[180:183], v[196:199], v[34:37]
	v_mfma_f32_16x16x32_bf16 v[18:21], v[176:179], v[206:209], v[18:21]
	v_mfma_f32_16x16x32_bf16 v[18:21], v[180:183], v[210:213], v[18:21]
	v_mfma_f32_16x16x32_bf16 v[2:5], v[176:179], v[214:217], v[2:5]
	v_mfma_f32_16x16x32_bf16 v[2:5], v[180:183], v[218:221], v[2:5]
	s_setprio 0
	s_barrier
	s_add_i32 m0, s1, 0x4000
	ds_read_b128 v[146:149], v226
	global_load_lds_dwordx4 v130, s[100:101]
	s_add_i32 m0, s1, 0x6000
	ds_read_b128 v[156:159], v226 offset:1024
	global_load_lds_dwordx4 v134, s[100:101]
	ds_read_b128 v[160:163], v226 offset:2048
	ds_read_b128 v[164:167], v226 offset:3072
	ds_read_b128 v[168:171], v227
	ds_read_b128 v[172:175], v227 offset:1024
	ds_read_b128 v[176:179], v227 offset:2048
	ds_read_b128 v[180:183], v227 offset:3072
	ds_read_b128 v[184:187], v154 offset:32768
	ds_read_b128 v[188:191], v154 offset:33792
	ds_read_b128 v[192:195], v154 offset:34816
	ds_read_b128 v[196:199], v154 offset:35840
	ds_read_b128 v[206:209], v154 offset:36864
	ds_read_b128 v[210:213], v154 offset:37888
	ds_read_b128 v[214:217], v154 offset:38912
	ds_read_b128 v[218:221], v154 offset:39936
	s_waitcnt vmcnt(8) lgkmcnt(0)
	s_barrier
	s_setprio 1
	v_mfma_f32_16x16x32_bf16 v[126:129], v[146:149], v[184:187], v[126:129]
	v_mfma_f32_16x16x32_bf16 v[126:129], v[156:159], v[188:191], v[126:129]
	v_mfma_f32_16x16x32_bf16 v[110:113], v[146:149], v[192:195], v[110:113]
	v_mfma_f32_16x16x32_bf16 v[110:113], v[156:159], v[196:199], v[110:113]
	v_mfma_f32_16x16x32_bf16 v[94:97], v[146:149], v[206:209], v[94:97]
	v_mfma_f32_16x16x32_bf16 v[94:97], v[156:159], v[210:213], v[94:97]
	v_mfma_f32_16x16x32_bf16 v[78:81], v[146:149], v[214:217], v[78:81]
	v_mfma_f32_16x16x32_bf16 v[78:81], v[156:159], v[218:221], v[78:81]
	v_mfma_f32_16x16x32_bf16 v[122:125], v[160:163], v[184:187], v[122:125]
	v_mfma_f32_16x16x32_bf16 v[122:125], v[164:167], v[188:191], v[122:125]
	v_mfma_f32_16x16x32_bf16 v[106:109], v[160:163], v[192:195], v[106:109]
	v_mfma_f32_16x16x32_bf16 v[106:109], v[164:167], v[196:199], v[106:109]
	v_mfma_f32_16x16x32_bf16 v[90:93], v[160:163], v[206:209], v[90:93]
	v_mfma_f32_16x16x32_bf16 v[90:93], v[164:167], v[210:213], v[90:93]
	v_mfma_f32_16x16x32_bf16 v[74:77], v[160:163], v[214:217], v[74:77]
	v_mfma_f32_16x16x32_bf16 v[74:77], v[164:167], v[218:221], v[74:77]
	v_mfma_f32_16x16x32_bf16 v[118:121], v[168:171], v[184:187], v[118:121]
	v_mfma_f32_16x16x32_bf16 v[118:121], v[172:175], v[188:191], v[118:121]
	v_mfma_f32_16x16x32_bf16 v[102:105], v[168:171], v[192:195], v[102:105]
	v_mfma_f32_16x16x32_bf16 v[102:105], v[172:175], v[196:199], v[102:105]
	v_mfma_f32_16x16x32_bf16 v[86:89], v[168:171], v[206:209], v[86:89]
	v_mfma_f32_16x16x32_bf16 v[86:89], v[172:175], v[210:213], v[86:89]
	v_mfma_f32_16x16x32_bf16 v[70:73], v[168:171], v[214:217], v[70:73]
	v_mfma_f32_16x16x32_bf16 v[70:73], v[172:175], v[218:221], v[70:73]
	v_mfma_f32_16x16x32_bf16 v[114:117], v[176:179], v[184:187], v[114:117]
	v_mfma_f32_16x16x32_bf16 v[114:117], v[180:183], v[188:191], v[114:117]
	v_mfma_f32_16x16x32_bf16 v[98:101], v[176:179], v[192:195], v[98:101]
	v_mfma_f32_16x16x32_bf16 v[98:101], v[180:183], v[196:199], v[98:101]
	v_mfma_f32_16x16x32_bf16 v[82:85], v[176:179], v[206:209], v[82:85]
	v_mfma_f32_16x16x32_bf16 v[82:85], v[180:183], v[210:213], v[82:85]
	v_mfma_f32_16x16x32_bf16 v[66:69], v[176:179], v[214:217], v[66:69]
	v_mfma_f32_16x16x32_bf16 v[66:69], v[180:183], v[218:221], v[66:69]
	s_setprio 0
	s_barrier
	s_add_i32 m0, s1, 0x18000
	ds_read_b128 v[184:187], v154 offset:49152
	global_load_lds_dwordx4 v132, s[98:99]
	s_add_i32 m0, s1, 0x1a000
	ds_read_b128 v[188:191], v154 offset:50176
	global_load_lds_dwordx4 v136, s[98:99]
	s_add_i32 m0, s1, 0x1c000
	ds_read_b128 v[192:195], v154 offset:51200
	global_load_lds_dwordx4 v132, s[24:25]
	s_add_i32 m0, s1, 0x1e000
	ds_read_b128 v[196:199], v154 offset:52224
	global_load_lds_dwordx4 v136, s[24:25]
	s_add_i32 m0, s1, 0x8000
	ds_read_b128 v[206:209], v154 offset:53248
	global_load_lds_dwordx4 v130, s[44:45]
	s_add_i32 m0, s1, 0xa000
	ds_read_b128 v[210:213], v154 offset:54272
	global_load_lds_dwordx4 v134, s[44:45]
	ds_read_b128 v[214:217], v154 offset:55296
	ds_read_b128 v[218:221], v154 offset:56320
	s_waitcnt vmcnt(8) lgkmcnt(0)
	s_barrier
	s_setprio 1
	v_mfma_f32_16x16x32_bf16 v[62:65], v[146:149], v[184:187], v[62:65]
	v_mfma_f32_16x16x32_bf16 v[62:65], v[156:159], v[188:191], v[62:65]
	v_mfma_f32_16x16x32_bf16 v[46:49], v[146:149], v[192:195], v[46:49]
	v_mfma_f32_16x16x32_bf16 v[46:49], v[156:159], v[196:199], v[46:49]
	v_mfma_f32_16x16x32_bf16 v[30:33], v[146:149], v[206:209], v[30:33]
	v_mfma_f32_16x16x32_bf16 v[30:33], v[156:159], v[210:213], v[30:33]
	v_mfma_f32_16x16x32_bf16 v[14:17], v[146:149], v[214:217], v[14:17]
	v_mfma_f32_16x16x32_bf16 v[14:17], v[156:159], v[218:221], v[14:17]
	v_mfma_f32_16x16x32_bf16 v[58:61], v[160:163], v[184:187], v[58:61]
	v_mfma_f32_16x16x32_bf16 v[58:61], v[164:167], v[188:191], v[58:61]
	v_mfma_f32_16x16x32_bf16 v[42:45], v[160:163], v[192:195], v[42:45]
	v_mfma_f32_16x16x32_bf16 v[42:45], v[164:167], v[196:199], v[42:45]
	v_mfma_f32_16x16x32_bf16 v[26:29], v[160:163], v[206:209], v[26:29]
	v_mfma_f32_16x16x32_bf16 v[26:29], v[164:167], v[210:213], v[26:29]
	v_mfma_f32_16x16x32_bf16 v[10:13], v[160:163], v[214:217], v[10:13]
	v_mfma_f32_16x16x32_bf16 v[10:13], v[164:167], v[218:221], v[10:13]
	v_mfma_f32_16x16x32_bf16 v[54:57], v[168:171], v[184:187], v[54:57]
	v_mfma_f32_16x16x32_bf16 v[54:57], v[172:175], v[188:191], v[54:57]
	v_mfma_f32_16x16x32_bf16 v[38:41], v[168:171], v[192:195], v[38:41]
	v_mfma_f32_16x16x32_bf16 v[38:41], v[172:175], v[196:199], v[38:41]
	s_add_i32 s61, s61, 2
	v_mfma_f32_16x16x32_bf16 v[22:25], v[168:171], v[206:209], v[22:25]
	v_mfma_f32_16x16x32_bf16 v[22:25], v[172:175], v[210:213], v[22:25]
	s_add_u32 s59, s59, 0x100000
	v_mfma_f32_16x16x32_bf16 v[6:9], v[168:171], v[214:217], v[6:9]
	v_mfma_f32_16x16x32_bf16 v[6:9], v[172:175], v[218:221], v[6:9]
	s_addc_u32 s60, s60, 0
	v_mfma_f32_16x16x32_bf16 v[50:53], v[176:179], v[184:187], v[50:53]
	v_mfma_f32_16x16x32_bf16 v[50:53], v[180:183], v[188:191], v[50:53]
	s_add_u32 s42, s42, 0x400000
	v_mfma_f32_16x16x32_bf16 v[34:37], v[176:179], v[192:195], v[34:37]
	v_mfma_f32_16x16x32_bf16 v[34:37], v[180:183], v[196:199], v[34:37]
	s_addc_u32 s43, s43, 0
	v_mfma_f32_16x16x32_bf16 v[18:21], v[176:179], v[206:209], v[18:21]
	v_mfma_f32_16x16x32_bf16 v[18:21], v[180:183], v[210:213], v[18:21]
	s_cmpk_gt_u32 s61, 0xa9
	v_mfma_f32_16x16x32_bf16 v[2:5], v[176:179], v[214:217], v[2:5]
	v_mfma_f32_16x16x32_bf16 v[2:5], v[180:183], v[218:221], v[2:5]
	s_setprio 0
	s_barrier
	s_cbranch_scc0 .LBB0_834
	s_and_b64 vcc, exec, s[18:19]
	s_cbranch_vccz .LBB0_837
	s_barrier
